# attention: K and V fragment LDS reads prefetched 4-5 MFMAs ahead, softmax VALU spread across PV MFMA gaps; gdn_prep/hyconv/hyena HFB loads batched
# speedup vs baseline: 1.0855x; 1.0271x over previous
; DI float siluf_(float x) { return x / (1.f + __expf(-x)); }
; DI void phase_gdn_prep(const Ctx& c) {
;     ...
;   for (int tok = blockIdx.x * 8 + wave; tok < T; tok += gridDim.x * 8) {
;     const int n = tok & (L - 1);
; #pragma unroll
;     for (int part = 0; part < 3; ++part) {
;       const int col = part * 512 + lane * 8;
;       float cur[8], prv[8], nxt[8], v[8];
;       unpack8(*(const uint4*)(P + (size_t)tok * 1536 + col), cur);
;       if (n > 0) unpack8(*(const uint4*)(P + (size_t)(tok - 1) * 1536 + col), prv);
;       else { for (int e = 0; e < 8; ++e) prv[e] = 0.f; }
;       if (n < L - 1) unpack8(*(const uint4*)(P + (size_t)(tok + 1) * 1536 + col), nxt);
;       else { for (int e = 0; e < 8; ++e) nxt[e] = 0.f; }
;       float ss = 0.f;
; #pragma unroll
;       for (int e = 0; e < 8; ++e) {
;         const float x = prv[e] * cw[col + e] + cur[e] * cw[1536 + col + e] + nxt[e] * cw[3072 + col + e];
;         v[e] = siluf_(x); ss += v[e] * v[e];
;       }
;       if (part < 2) {
;         ss += __shfl_xor(ss, 1); ss += __shfl_xor(ss, 2); ss += __shfl_xor(ss, 4); ss += __shfl_xor(ss, 8);
;         float inv = rsqrtf(ss + EPS);
;         if (part == 0) inv *= 0.08838834764831845f;
; #pragma unroll
;         for (int e = 0; e < 8; ++e) v[e] *= inv;
;       }
;       bf16* dst = (bf16*)(c.ws + OFF_GQ + (size_t)part * SZ_T512) + (size_t)tok * 512 + lane * 8;
;       *(uint4*)dst = pack8(v);
.LBB0_304:
	s_movk_i32 s10, 0xc00
	v_mad_i64_i32 v[44:45], s[6:7], v6, s10, v[40:41]
	global_load_dwordx4 v[2:5], v[44:45], off
	v_readlane_b32 s8, v228, 2
	v_readlane_b32 s6, v226, 16
	v_readlane_b32 s9, v228, 3
	v_add_u32_e32 v0, -1, v6
	v_and_b32_e32 v7, s6, v6
	v_mov_b64_e32 v[42:43], s[8:9]
	v_cmp_lt_i32_e64 s[6:7], 0, v7
	v_mad_i64_i32 v[42:43], s[8:9], v0, s10, v[42:43]
	v_mov_b32_e32 v48, 0
	v_lshlrev_b32_e32 v0, 1, v10
	v_mov_b32_e32 v50, 0
	v_mov_b32_e32 v51, 0
	v_mov_b32_e32 v52, 0
	v_mov_b32_e32 v53, 0
	v_mov_b32_e32 v54, 0
	v_mov_b32_e32 v55, 0
	v_mov_b32_e32 v56, 0
	v_mov_b32_e32 v57, 0
	v_mov_b32_e32 v230, 0
	v_mov_b32_e32 v231, 0
	v_mov_b32_e32 v232, 0
	v_mov_b32_e32 v233, 0
	v_mov_b32_e32 v234, 0
	v_mov_b32_e32 v235, 0
	v_mov_b32_e32 v236, 0
	v_mov_b32_e32 v237, 0
	s_and_saveexec_b64 s[8:9], s[6:7]
	s_cbranch_execz .LBB0_306
	v_lshl_add_u64 v[46:47], v[42:43], 0, v[0:1]
	global_load_dwordx4 v[230:233], v[46:47], off
.LBB0_306:
	s_or_b64 exec, exec, s[8:9]
	v_readlane_b32 s10, v228, 2
	v_readlane_b32 s8, v226, 16
	v_readlane_b32 s11, v228, 3
	v_mov_b32_e32 v49, 0
	v_cmp_gt_i32_e64 s[8:9], s8, v7
	v_add_u32_e32 v7, 1, v6
	v_mov_b64_e32 v[46:47], s[10:11]
	s_movk_i32 s10, 0xc00
	v_mad_i64_i32 v[46:47], s[10:11], v7, s10, v[46:47]
	v_mov_b32_e32 v58, 0
	v_mov_b32_e32 v59, 0
	v_mov_b32_e32 v60, 0
	v_mov_b32_e32 v61, 0
	v_mov_b32_e32 v62, 0
	v_mov_b32_e32 v63, 0
	s_and_saveexec_b64 s[10:11], s[8:9]
	s_cbranch_execz .LBB0_308
	v_lshl_add_u64 v[48:49], v[46:47], 0, v[0:1]
	global_load_dwordx4 v[234:237], v[48:49], off
.LBB0_308:
	s_or_b64 exec, exec, s[10:11]
	global_load_dwordx4 v[68:71], v[20:21], off offset:16
	global_load_dwordx4 v[72:75], v[20:21], off
	global_load_dwordx4 v[76:79], v[18:19], off offset:16
	global_load_dwordx4 v[80:83], v[18:19], off
	global_load_dwordx4 v[84:87], v[22:23], off offset:16
	global_load_dwordx4 v[88:91], v[22:23], off
	s_waitcnt vmcnt(0)
	v_lshlrev_b32_e32 v50, 16, v230
	v_and_b32_e32 v51, 0xffff0000, v230
	v_lshlrev_b32_e32 v52, 16, v231
	v_and_b32_e32 v53, 0xffff0000, v231
	v_lshlrev_b32_e32 v54, 16, v232
	v_and_b32_e32 v55, 0xffff0000, v232
	v_lshlrev_b32_e32 v56, 16, v233
	v_and_b32_e32 v57, 0xffff0000, v233
	v_lshlrev_b32_e32 v48, 16, v234
	v_and_b32_e32 v49, 0xffff0000, v234
	v_lshlrev_b32_e32 v58, 16, v235
	v_and_b32_e32 v59, 0xffff0000, v235
	v_lshlrev_b32_e32 v60, 16, v236
	v_and_b32_e32 v61, 0xffff0000, v236
	v_lshlrev_b32_e32 v62, 16, v237
	v_and_b32_e32 v63, 0xffff0000, v237
	v_lshlrev_b32_e32 v94, 16, v4
	v_and_b32_e32 v95, 0xffff0000, v4
	v_lshlrev_b32_e32 v4, 16, v5
	v_and_b32_e32 v5, 0xffff0000, v5
	v_lshlrev_b32_e32 v92, 16, v3
	v_and_b32_e32 v93, 0xffff0000, v3
	v_lshlrev_b32_e32 v64, 16, v2
	v_and_b32_e32 v65, 0xffff0000, v2
	v_pk_mul_f32 v[4:5], v[70:71], v[4:5]
	v_pk_mul_f32 v[68:69], v[68:69], v[94:95]
	v_pk_fma_f32 v[4:5], v[56:57], v[78:79], v[4:5]
	v_pk_mul_f32 v[70:71], v[74:75], v[92:93]
	v_pk_fma_f32 v[4:5], v[62:63], v[86:87], v[4:5]
	v_pk_fma_f32 v[54:55], v[54:55], v[76:77], v[68:69]
	v_pk_fma_f32 v[52:53], v[52:53], v[82:83], v[70:71]
	v_mul_f32_e32 v3, 0xbfb8aa3b, v4
	v_mul_f32_e32 v7, 0xbfb8aa3b, v5
	v_pk_fma_f32 v[54:55], v[60:61], v[84:85], v[54:55]
	v_pk_fma_f32 v[52:53], v[58:59], v[90:91], v[52:53]
	v_exp_f32_e32 v56, v3
	v_exp_f32_e32 v57, v7
	v_mul_f32_e32 v58, 0xbfb8aa3b, v54
	v_mul_f32_e32 v59, 0xbfb8aa3b, v55
	v_mul_f32_e32 v60, 0xbfb8aa3b, v52
	v_mul_f32_e32 v61, 0xbfb8aa3b, v53
	v_exp_f32_e32 v58, v58
	v_exp_f32_e32 v59, v59
	v_exp_f32_e32 v60, v60
	v_exp_f32_e32 v61, v61
	v_pk_add_f32 v[2:3], v[56:57], 1.0 op_sel_hi:[1,0]
	v_pk_add_f32 v[56:57], v[58:59], 1.0 op_sel_hi:[1,0]
	v_div_scale_f32 v7, s[10:11], v3, v3, v5
	v_pk_add_f32 v[58:59], v[60:61], 1.0 op_sel_hi:[1,0]
	v_div_scale_f32 v61, s[10:11], v2, v2, v4
	v_rcp_f32_e32 v75, v7
	v_rcp_f32_e32 v76, v61
	v_div_scale_f32 v63, s[12:13], v57, v57, v55
	v_div_scale_f32 v69, s[14:15], v56, v56, v54
	v_rcp_f32_e32 v77, v63
	v_rcp_f32_e32 v78, v69
	v_fma_f32 v82, -v7, v75, 1.0
	v_div_scale_f32 v60, vcc, v5, v3, v5
	v_div_scale_f32 v71, s[16:17], v59, v59, v53
	v_fma_f32 v83, -v61, v76, 1.0
	v_fmac_f32_e32 v75, v82, v75
	v_div_scale_f32 v62, s[10:11], v4, v2, v4
	v_rcp_f32_e32 v79, v71
	v_fmac_f32_e32 v76, v83, v76
	v_mul_f32_e32 v82, v60, v75
	v_fma_f32 v84, -v63, v77, 1.0
	v_mul_f32_e32 v83, v62, v76
	v_fma_f32 v87, -v7, v82, v60
	v_div_scale_f32 v68, s[12:13], v55, v57, v55
	v_fma_f32 v85, -v69, v78, 1.0
	v_fmac_f32_e32 v77, v84, v77
	v_fma_f32 v90, -v61, v83, v62
	v_fmac_f32_e32 v82, v87, v75
	v_div_scale_f32 v70, s[14:15], v54, v56, v54
	v_fmac_f32_e32 v78, v85, v78
	v_mul_f32_e32 v84, v68, v77
	v_fmac_f32_e32 v83, v90, v76
	v_fma_f32 v7, -v7, v82, v60
	v_fma_f32 v86, -v71, v79, 1.0
	v_mul_f32_e32 v85, v70, v78
	v_fma_f32 v91, -v63, v84, v68
	v_fma_f32 v60, -v61, v83, v62
	v_div_fmas_f32 v7, v7, v75, v82
	s_mov_b64 vcc, s[10:11]
	v_div_scale_f32 v74, s[16:17], v53, v59, v53
	v_fmac_f32_e32 v79, v86, v79
	v_fma_f32 v92, -v69, v85, v70
	v_fmac_f32_e32 v84, v91, v77
	v_div_fixup_f32 v61, v7, v3, v5
	v_div_fmas_f32 v3, v60, v76, v83
	v_mul_f32_e32 v86, v74, v79
	v_fmac_f32_e32 v85, v92, v78
	v_fma_f32 v62, -v63, v84, v68
	v_div_fixup_f32 v60, v3, v2, v4
	s_mov_b64 vcc, s[12:13]
	v_div_scale_f32 v4, s[10:11], v58, v58, v52
	v_fma_f32 v93, -v71, v86, v74
	v_fma_f32 v68, -v69, v85, v70
	v_div_fmas_f32 v2, v62, v77, v84
	s_mov_b64 vcc, s[14:15]
	v_rcp_f32_e32 v5, v4
	v_fmac_f32_e32 v86, v93, v79
	v_div_fixup_f32 v55, v2, v57, v55
	v_div_fmas_f32 v2, v68, v78, v85
	v_div_fixup_f32 v54, v2, v56, v54
	v_fma_f32 v2, -v71, v86, v74
	s_mov_b64 vcc, s[16:17]
	v_div_fmas_f32 v2, v2, v79, v86
; DI float siluf_(float x) { return x / (1.f + __expf(-x)); }
; DI void phase_gdn_prep(const Ctx& c) {
;     ...
;       float ss = 0.f;
; #pragma unroll
;       for (int e = 0; e < 8; ++e) {
;         const float x = prv[e] * cw[col + e] + cur[e] * cw[1536 + col + e] + nxt[e] * cw[3072 + col + e];
;         v[e] = siluf_(x); ss += v[e] * v[e];
;       }
;       if (part < 2) {
;         ss += __shfl_xor(ss, 1); ss += __shfl_xor(ss, 2); ss += __shfl_xor(ss, 4); ss += __shfl_xor(ss, 8);
;         float inv = rsqrtf(ss + EPS);
;         if (part == 0) inv *= 0.08838834764831845f;
; #pragma unroll
;         for (int e = 0; e < 8; ++e) v[e] *= inv;
;       }
;       bf16* dst = (bf16*)(c.ws + OFF_GQ + (size_t)part * SZ_T512) + (size_t)tok * 512 + lane * 8;
;       *(uint4*)dst = pack8(v);
	v_div_fixup_f32 v53, v2, v59, v53
	v_fma_f32 v2, -v4, v5, 1.0
	v_fmac_f32_e32 v5, v2, v5
	v_pk_mul_f32 v[2:3], v[72:73], v[64:65]
	v_div_scale_f32 v7, vcc, v52, v58, v52
	v_pk_fma_f32 v[2:3], v[50:51], v[80:81], v[2:3]
	v_mul_f32_e32 v59, v7, v5
	v_pk_fma_f32 v[48:49], v[48:49], v[88:89], v[2:3]
	v_fma_f32 v50, -v4, v59, v7
	v_mul_f32_e32 v2, 0xbfb8aa3b, v48
	v_mul_f32_e32 v3, 0xbfb8aa3b, v49
	v_exp_f32_e32 v2, v2
	v_exp_f32_e32 v3, v3
	v_fmac_f32_e32 v59, v50, v5
	v_fma_f32 v4, -v4, v59, v7
	v_pk_mul_f32 v[56:57], v[54:55], v[54:55]
	v_pk_add_f32 v[50:51], v[2:3], 1.0 op_sel_hi:[1,0]
	v_div_fmas_f32 v2, v4, v5, v59
	v_div_scale_f32 v7, s[10:11], v51, v51, v49
	v_rcp_f32_e32 v64, v7
	v_div_fixup_f32 v52, v2, v58, v52
	v_div_scale_f32 v65, vcc, v49, v51, v49
	v_fma_f32 v2, -v7, v64, 1.0
	v_fmac_f32_e32 v64, v2, v64
	v_mul_f32_e32 v68, v65, v64
	v_fma_f32 v2, -v7, v68, v65
	v_fmac_f32_e32 v68, v2, v64
	global_load_dwordx4 v[2:5], v[44:45], off offset:1024
	v_fma_f32 v7, -v7, v68, v65
	v_div_scale_f32 v65, s[10:11], v50, v50, v48
	v_rcp_f32_e32 v69, v65
	v_div_fmas_f32 v7, v7, v64, v68
	v_div_fixup_f32 v51, v7, v51, v49
	v_pk_mul_f32 v[58:59], v[52:53], v[52:53]
	v_fma_f32 v7, -v65, v69, 1.0
	v_fmac_f32_e32 v69, v7, v69
	v_div_scale_f32 v7, vcc, v48, v50, v48
	v_mul_f32_e32 v49, v7, v69
	v_fma_f32 v64, -v65, v49, v7
	v_fmac_f32_e32 v49, v64, v69
	v_fma_f32 v7, -v65, v49, v7
	v_div_fmas_f32 v7, v7, v69, v49
	v_div_fixup_f32 v50, v7, v50, v48
	v_pk_mul_f32 v[48:49], v[50:51], v[50:51]
	v_pk_mul_f32 v[62:63], v[60:61], v[60:61]
	v_add_f32_e32 v7, v48, v49
	v_add_f32_e32 v7, v7, v58
	v_add_f32_e32 v7, v7, v59
	v_add_f32_e32 v7, v7, v56
	v_add_f32_e32 v7, v7, v57
	v_add_f32_e32 v7, v7, v62
	v_add_f32_e32 v7, v7, v63
	ds_bpermute_b32 v48, v9, v7
	s_mov_b32 s10, 0x800000
	s_waitcnt lgkmcnt(0)
	v_add_f32_e32 v7, v7, v48
	ds_bpermute_b32 v48, v11, v7
	s_waitcnt lgkmcnt(0)
	v_add_f32_e32 v7, v7, v48
	ds_bpermute_b32 v48, v66, v7
	s_waitcnt lgkmcnt(0)
	v_add_f32_e32 v7, v7, v48
	ds_bpermute_b32 v48, v67, v7
	s_waitcnt lgkmcnt(0)
	v_add_f32_e32 v7, v7, v48
	v_add_f32_e32 v7, 0x358637bd, v7
	v_mul_f32_e32 v48, 0x4b800000, v7
	v_cmp_gt_f32_e32 vcc, s10, v7
	s_nop 1
	v_cndmask_b32_e32 v7, v7, v48, vcc
	v_rsq_f32_e32 v58, v7
	v_ashrrev_i32_e32 v7, 31, v6
	v_lshlrev_b64 v[48:49], 10, v[6:7]
	v_lshl_add_u64 v[56:57], v[34:35], 0, v[48:49]
	v_mul_f32_e32 v59, 0x45800000, v58
	v_cndmask_b32_e32 v58, v58, v59, vcc
	v_mul_f32_e32 v58, 0x3db504f3, v58
	v_pk_mul_f32 v[60:61], v[60:61], v[58:59] op_sel_hi:[1,0]
	v_pk_mul_f32 v[54:55], v[54:55], v[58:59] op_sel_hi:[1,0]
	v_pk_mul_f32 v[52:53], v[52:53], v[58:59] op_sel_hi:[1,0]
	v_pk_mul_f32 v[50:51], v[50:51], v[58:59] op_sel_hi:[1,0]
	v_mov_b32_e32 v58, 0
	v_cvt_pk_bf16_f32 v50, v50, v51
	v_cvt_pk_bf16_f32 v51, v52, v53
	v_cvt_pk_bf16_f32 v52, v54, v55
	v_cvt_pk_bf16_f32 v53, v60, v61
	global_store_dwordx4 v[56:57], v[50:53], off
	v_mov_b32_e32 v54, 0
	v_mov_b32_e32 v55, 0
	v_mov_b32_e32 v50, 0
	v_mov_b32_e32 v52, 0
	v_mov_b32_e32 v53, 0
	v_mov_b32_e32 v56, 0
	v_mov_b32_e32 v57, 0
	v_mov_b32_e32 v59, 0
	v_mov_b32_e32 v230, 0
	v_mov_b32_e32 v231, 0
	v_mov_b32_e32 v232, 0
	v_mov_b32_e32 v233, 0
	v_mov_b32_e32 v234, 0
	v_mov_b32_e32 v235, 0
	v_mov_b32_e32 v236, 0
	v_mov_b32_e32 v237, 0
	s_and_saveexec_b64 s[10:11], s[6:7]
	s_cbranch_execz .LBB0_310
	v_lshl_add_u64 v[52:53], v[42:43], 0, v[0:1]
	global_load_dwordx4 v[230:233], v[52:53], off offset:1024
.LBB0_310:
	s_or_b64 exec, exec, s[10:11]
	v_mov_b32_e32 v51, 0
	v_mov_b32_e32 v60, 0
	v_mov_b32_e32 v61, 0
	v_mov_b32_e32 v62, 0
	v_mov_b32_e32 v63, 0
	v_mov_b32_e32 v64, 0
	v_mov_b32_e32 v65, 0
	s_and_saveexec_b64 s[10:11], s[8:9]
	s_cbranch_execz .LBB0_312
	v_lshl_add_u64 v[50:51], v[46:47], 0, v[0:1]
	global_load_dwordx4 v[234:237], v[50:51], off offset:1024
.LBB0_312:
	s_or_b64 exec, exec, s[10:11]
	global_load_dwordx4 v[68:71], v[24:25], off offset:16
	global_load_dwordx4 v[72:75], v[24:25], off
	global_load_dwordx4 v[76:79], v[18:19], off offset:2064
	global_load_dwordx4 v[80:83], v[18:19], off offset:2048
	global_load_dwordx4 v[84:87], v[26:27], off offset:16
	global_load_dwordx4 v[88:91], v[26:27], off
	s_waitcnt vmcnt(7)
	v_lshlrev_b32_e32 v96, 16, v4
	v_and_b32_e32 v97, 0xffff0000, v4
	v_lshlrev_b32_e32 v4, 16, v5
	v_and_b32_e32 v5, 0xffff0000, v5
	v_lshlrev_b32_e32 v94, 16, v3
	v_and_b32_e32 v95, 0xffff0000, v3
	v_lshlrev_b32_e32 v92, 16, v2
	v_and_b32_e32 v93, 0xffff0000, v2
	s_waitcnt vmcnt(5)
	v_lshlrev_b32_e32 v52, 16, v230
	v_and_b32_e32 v53, 0xffff0000, v230
	v_lshlrev_b32_e32 v54, 16, v231
	v_and_b32_e32 v55, 0xffff0000, v231
	v_lshlrev_b32_e32 v56, 16, v232
	v_and_b32_e32 v57, 0xffff0000, v232
	v_lshlrev_b32_e32 v58, 16, v233
	v_and_b32_e32 v59, 0xffff0000, v233
	v_lshlrev_b32_e32 v50, 16, v234
	v_and_b32_e32 v51, 0xffff0000, v234
	v_lshlrev_b32_e32 v60, 16, v235
	v_and_b32_e32 v61, 0xffff0000, v235
	v_lshlrev_b32_e32 v62, 16, v236
	v_and_b32_e32 v63, 0xffff0000, v236
	v_lshlrev_b32_e32 v64, 16, v237
	v_and_b32_e32 v65, 0xffff0000, v237
	v_pk_mul_f32 v[4:5], v[70:71], v[4:5]
	v_pk_mul_f32 v[68:69], v[68:69], v[96:97]
	s_waitcnt vmcnt(4)
	v_pk_mul_f32 v[70:71], v[74:75], v[94:95]
	s_waitcnt vmcnt(3)
	v_pk_fma_f32 v[4:5], v[58:59], v[78:79], v[4:5]
	v_pk_fma_f32 v[56:57], v[56:57], v[76:77], v[68:69]
	s_waitcnt vmcnt(2)
	v_pk_fma_f32 v[54:55], v[54:55], v[82:83], v[70:71]
	s_waitcnt vmcnt(1)
	v_pk_fma_f32 v[4:5], v[64:65], v[86:87], v[4:5]
	v_pk_fma_f32 v[56:57], v[62:63], v[84:85], v[56:57]
	s_waitcnt vmcnt(0)
; DI float siluf_(float x) { return x / (1.f + __expf(-x)); }
; DI void phase_gdn_prep(const Ctx& c) {
;     ...
;       float ss = 0.f;
; #pragma unroll
;       for (int e = 0; e < 8; ++e) {
;         const float x = prv[e] * cw[col + e] + cur[e] * cw[1536 + col + e] + nxt[e] * cw[3072 + col + e];
;         v[e] = siluf_(x); ss += v[e] * v[e];
;       }
;       if (part < 2) {
;         ss += __shfl_xor(ss, 1); ss += __shfl_xor(ss, 2); ss += __shfl_xor(ss, 4); ss += __shfl_xor(ss, 8);
;         float inv = rsqrtf(ss + EPS);
;         if (part == 0) inv *= 0.08838834764831845f;
; #pragma unroll
;         for (int e = 0; e < 8; ++e) v[e] *= inv;
;       }
;       bf16* dst = (bf16*)(c.ws + OFF_GQ + (size_t)part * SZ_T512) + (size_t)tok * 512 + lane * 8;
;       *(uint4*)dst = pack8(v);
	v_pk_fma_f32 v[54:55], v[60:61], v[90:91], v[54:55]
	v_mul_f32_e32 v3, 0xbfb8aa3b, v4
	v_mul_f32_e32 v59, 0xbfb8aa3b, v5
	v_mul_f32_e32 v60, 0xbfb8aa3b, v56
	v_mul_f32_e32 v61, 0xbfb8aa3b, v57
	v_mul_f32_e32 v62, 0xbfb8aa3b, v54
	v_mul_f32_e32 v63, 0xbfb8aa3b, v55
	v_exp_f32_e32 v58, v3
	v_exp_f32_e32 v59, v59
	v_exp_f32_e32 v60, v60
	v_exp_f32_e32 v61, v61
	v_exp_f32_e32 v62, v62
	v_exp_f32_e32 v63, v63
	v_pk_add_f32 v[2:3], v[58:59], 1.0 op_sel_hi:[1,0]
	v_pk_add_f32 v[58:59], v[60:61], 1.0 op_sel_hi:[1,0]
	v_div_scale_f32 v64, s[10:11], v2, v2, v4
	v_pk_add_f32 v[60:61], v[62:63], 1.0 op_sel_hi:[1,0]
	v_div_scale_f32 v62, s[10:11], v3, v3, v5
	v_rcp_f32_e32 v76, v62
	v_div_scale_f32 v68, s[12:13], v59, v59, v57
	v_rcp_f32_e32 v77, v64
	v_div_scale_f32 v70, s[14:15], v58, v58, v56
	v_rcp_f32_e32 v78, v68
	v_div_scale_f32 v74, s[16:17], v61, v61, v55
	v_rcp_f32_e32 v79, v70
	v_rcp_f32_e32 v82, v74
	v_fma_f32 v83, -v62, v76, 1.0
	v_div_scale_f32 v63, vcc, v5, v3, v5
	v_fma_f32 v84, -v64, v77, 1.0
	v_fmac_f32_e32 v76, v83, v76
	v_div_scale_f32 v65, s[10:11], v4, v2, v4
	v_fma_f32 v85, -v68, v78, 1.0
	v_fmac_f32_e32 v77, v84, v77
	v_mul_f32_e32 v83, v63, v76
	v_div_scale_f32 v69, s[12:13], v57, v59, v57
	v_fma_f32 v86, -v70, v79, 1.0
	v_fmac_f32_e32 v78, v85, v78
	v_mul_f32_e32 v84, v65, v77
	v_fma_f32 v90, -v62, v83, v63
	v_div_scale_f32 v71, s[14:15], v56, v58, v56
	v_fma_f32 v87, -v74, v82, 1.0
	v_fmac_f32_e32 v79, v86, v79
	v_mul_f32_e32 v85, v69, v78
	v_fma_f32 v91, -v64, v84, v65
	v_fmac_f32_e32 v83, v90, v76
	v_div_scale_f32 v75, s[16:17], v55, v61, v55
	v_fmac_f32_e32 v82, v87, v82
	v_mul_f32_e32 v86, v71, v79
	v_fma_f32 v94, -v68, v85, v69
	v_fmac_f32_e32 v84, v91, v77
	v_fma_f32 v62, -v62, v83, v63
	v_mul_f32_e32 v87, v75, v82
	v_fma_f32 v95, -v70, v86, v71
	v_fmac_f32_e32 v85, v94, v78
	v_fma_f32 v63, -v64, v84, v65
	v_div_fmas_f32 v62, v62, v76, v83
	s_mov_b64 vcc, s[10:11]
	v_fma_f32 v96, -v74, v87, v75
	v_fmac_f32_e32 v86, v95, v79
	v_fma_f32 v64, -v68, v85, v69
	v_div_fixup_f32 v3, v62, v3, v5
	v_div_fmas_f32 v5, v63, v77, v84
	s_mov_b64 vcc, s[12:13]
	v_fmac_f32_e32 v87, v96, v82
	v_fma_f32 v65, -v70, v86, v71
	v_div_fmas_f32 v62, v64, v78, v85
	s_mov_b64 vcc, s[14:15]
	v_div_fixup_f32 v57, v62, v59, v57
	v_div_fmas_f32 v59, v65, v79, v86
	v_fma_f32 v62, -v74, v87, v75
	s_mov_b64 vcc, s[16:17]
	v_div_fmas_f32 v62, v62, v82, v87
	v_div_scale_f32 v64, s[10:11], v60, v60, v54
	v_div_fixup_f32 v55, v62, v61, v55
	v_pk_mul_f32 v[62:63], v[72:73], v[92:93]
	v_rcp_f32_e32 v65, v64
	v_pk_fma_f32 v[52:53], v[52:53], v[80:81], v[62:63]
	v_div_fixup_f32 v56, v59, v58, v56
	v_pk_fma_f32 v[50:51], v[50:51], v[88:89], v[52:53]
	v_fma_f32 v61, -v64, v65, 1.0
	v_mul_f32_e32 v52, 0xbfb8aa3b, v50
	v_mul_f32_e32 v53, 0xbfb8aa3b, v51
	v_exp_f32_e32 v52, v52
	v_exp_f32_e32 v53, v53
	v_fmac_f32_e32 v65, v61, v65
	v_div_scale_f32 v61, vcc, v54, v60, v54
	v_mul_f32_e32 v68, v61, v65
	v_fma_f32 v62, -v64, v68, v61
	v_pk_add_f32 v[52:53], v[52:53], 1.0 op_sel_hi:[1,0]
	v_fmac_f32_e32 v68, v62, v65
	v_div_scale_f32 v62, s[10:11], v53, v53, v51
	v_rcp_f32_e32 v63, v62
	v_fma_f32 v61, -v64, v68, v61
	v_div_fmas_f32 v61, v61, v65, v68
	v_div_fixup_f32 v54, v61, v60, v54
	v_fma_f32 v64, -v62, v63, 1.0
	v_fmac_f32_e32 v63, v64, v63
	v_div_scale_f32 v64, vcc, v51, v53, v51
	v_mul_f32_e32 v65, v64, v63
	v_fma_f32 v68, -v62, v65, v64
	v_fmac_f32_e32 v65, v68, v63
	v_fma_f32 v62, -v62, v65, v64
	v_div_scale_f32 v64, s[10:11], v52, v52, v50
	v_rcp_f32_e32 v68, v64
	v_div_fmas_f32 v62, v62, v63, v65
	v_div_fixup_f32 v51, v62, v53, v51
	v_pk_mul_f32 v[60:61], v[54:55], v[54:55]
	v_fma_f32 v53, -v64, v68, 1.0
	v_fmac_f32_e32 v68, v53, v68
	v_div_scale_f32 v53, vcc, v50, v52, v50
	v_mul_f32_e32 v62, v53, v68
	v_fma_f32 v63, -v64, v62, v53
	v_fmac_f32_e32 v62, v63, v68
	v_fma_f32 v53, -v64, v62, v53
	v_div_fmas_f32 v53, v53, v68, v62
	v_div_fixup_f32 v50, v53, v52, v50
	v_pk_mul_f32 v[52:53], v[50:51], v[50:51]
	v_pk_mul_f32 v[58:59], v[56:57], v[56:57]
	v_add_f32_e32 v52, v52, v53
	v_add_f32_e32 v52, v52, v60
	v_add_f32_e32 v52, v52, v61
	v_div_fixup_f32 v2, v5, v2, v4
	v_add_f32_e32 v52, v52, v58
	v_pk_mul_f32 v[4:5], v[2:3], v[2:3]
	v_add_f32_e32 v52, v52, v59
	v_add_f32_e32 v4, v52, v4
	v_add_f32_e32 v4, v4, v5
	ds_bpermute_b32 v5, v9, v4
	s_mov_b32 s10, 0x800000
	v_lshl_add_u64 v[52:53], v[36:37], 0, v[48:49]
	s_waitcnt lgkmcnt(0)
	v_add_f32_e32 v4, v4, v5
	ds_bpermute_b32 v5, v11, v4
	s_waitcnt lgkmcnt(0)
	v_add_f32_e32 v4, v4, v5
	ds_bpermute_b32 v5, v66, v4
	s_waitcnt lgkmcnt(0)
	v_add_f32_e32 v4, v4, v5
	ds_bpermute_b32 v5, v67, v4
	s_waitcnt lgkmcnt(0)
	v_add_f32_e32 v4, v4, v5
	v_add_f32_e32 v4, 0x358637bd, v4
	v_mul_f32_e32 v5, 0x4b800000, v4
	v_cmp_gt_f32_e32 vcc, s10, v4
	s_nop 1
	v_cndmask_b32_e32 v4, v4, v5, vcc
	v_rsq_f32_e32 v4, v4
	s_nop 0
	v_mul_f32_e32 v5, 0x45800000, v4
	v_cndmask_b32_e32 v4, v4, v5, vcc
	v_pk_mul_f32 v[50:51], v[50:51], v[4:5] op_sel_hi:[1,0]
	v_pk_mul_f32 v[54:55], v[54:55], v[4:5] op_sel_hi:[1,0]
	v_pk_mul_f32 v[56:57], v[56:57], v[4:5] op_sel_hi:[1,0]
	v_pk_mul_f32 v[58:59], v[2:3], v[4:5] op_sel_hi:[1,0]
	v_cvt_pk_bf16_f32 v2, v50, v51
	v_cvt_pk_bf16_f32 v3, v54, v55
	v_cvt_pk_bf16_f32 v4, v56, v57
	v_cvt_pk_bf16_f32 v5, v58, v59
	global_store_dwordx4 v[52:53], v[2:5], off
	global_load_dwordx4 v[2:5], v[44:45], off offset:2048
	v_mov_b32_e32 v50, 0
	v_mov_b32_e32 v52, 0
	v_mov_b32_e32 v53, 0
	v_mov_b32_e32 v54, 0
	v_mov_b32_e32 v55, 0
	v_mov_b32_e32 v56, 0
	v_mov_b32_e32 v57, 0
	v_mov_b32_e32 v44, 0
	v_mov_b32_e32 v45, 0
	v_mov_b32_e32 v230, 0
	v_mov_b32_e32 v231, 0
	v_mov_b32_e32 v232, 0
	v_mov_b32_e32 v233, 0
	v_mov_b32_e32 v234, 0
	v_mov_b32_e32 v235, 0
	v_mov_b32_e32 v236, 0
	v_mov_b32_e32 v237, 0
	s_and_saveexec_b64 s[10:11], s[6:7]
	s_cbranch_execz .LBB0_314
	v_lshl_add_u64 v[42:43], v[42:43], 0, v[0:1]
	global_load_dwordx4 v[230:233], v[42:43], off offset:2048
; DI float siluf_(float x) { return x / (1.f + __expf(-x)); }
; DI void phase_gdn_prep(const Ctx& c) {
;     ...
;       const int col = part * 512 + lane * 8;
;       float cur[8], prv[8], nxt[8], v[8];
;       unpack8(*(const uint4*)(P + (size_t)tok * 1536 + col), cur);
;       if (n > 0) unpack8(*(const uint4*)(P + (size_t)(tok - 1) * 1536 + col), prv);
;       else { for (int e = 0; e < 8; ++e) prv[e] = 0.f; }
;       if (n < L - 1) unpack8(*(const uint4*)(P + (size_t)(tok + 1) * 1536 + col), nxt);
;       else { for (int e = 0; e < 8; ++e) nxt[e] = 0.f; }
;       float ss = 0.f;
; #pragma unroll
;       for (int e = 0; e < 8; ++e) {
;         const float x = prv[e] * cw[col + e] + cur[e] * cw[1536 + col + e] + nxt[e] * cw[3072 + col + e];
;         v[e] = siluf_(x); ss += v[e] * v[e];
;       }
;       if (part < 2) {
;         ss += __shfl_xor(ss, 1); ss += __shfl_xor(ss, 2); ss += __shfl_xor(ss, 4); ss += __shfl_xor(ss, 8);
;         float inv = rsqrtf(ss + EPS);
;         if (part == 0) inv *= 0.08838834764831845f;
; #pragma unroll
;         for (int e = 0; e < 8; ++e) v[e] *= inv;
;       }
;       bf16* dst = (bf16*)(c.ws + OFF_GQ + (size_t)part * SZ_T512) + (size_t)tok * 512 + lane * 8;
;       *(uint4*)dst = pack8(v);
;     }
.LBB0_314:
	s_or_b64 exec, exec, s[10:11]
	v_mov_b32_e32 v51, 0
	v_mov_b32_e32 v58, 0
	v_mov_b32_e32 v59, 0
	v_mov_b32_e32 v60, 0
	v_mov_b32_e32 v61, 0
	v_mov_b32_e32 v42, 0
	v_mov_b32_e32 v43, 0
	s_and_saveexec_b64 s[6:7], s[8:9]
	s_cbranch_execz .LBB0_316
	v_lshl_add_u64 v[42:43], v[46:47], 0, v[0:1]
	global_load_dwordx4 v[234:237], v[42:43], off offset:2048
.LBB0_316:
	s_or_b64 exec, exec, s[6:7]
	global_load_dwordx4 v[62:65], v[30:31], off
	global_load_dwordx4 v[68:71], v[30:31], off offset:16
	global_load_dwordx4 v[72:75], v[28:29], off
	global_load_dwordx4 v[76:79], v[28:29], off offset:16
	global_load_dwordx4 v[80:83], v[32:33], off
	global_load_dwordx4 v[84:87], v[32:33], off offset:16
	s_waitcnt vmcnt(6)
	v_lshlrev_b32_e32 v52, 16, v230
	v_and_b32_e32 v53, 0xffff0000, v230
	v_lshlrev_b32_e32 v54, 16, v231
	v_and_b32_e32 v55, 0xffff0000, v231
	v_lshlrev_b32_e32 v56, 16, v232
	v_and_b32_e32 v57, 0xffff0000, v232
	v_lshlrev_b32_e32 v44, 16, v233
	v_and_b32_e32 v45, 0xffff0000, v233
	v_lshlrev_b32_e32 v50, 16, v234
	v_and_b32_e32 v51, 0xffff0000, v234
	v_lshlrev_b32_e32 v58, 16, v235
	v_and_b32_e32 v59, 0xffff0000, v235
	v_lshlrev_b32_e32 v60, 16, v236
	v_and_b32_e32 v61, 0xffff0000, v236
	v_lshlrev_b32_e32 v42, 16, v237
	v_and_b32_e32 v43, 0xffff0000, v237
	v_lshlrev_b32_e32 v46, 16, v2
	v_and_b32_e32 v47, 0xffff0000, v2
	v_lshlrev_b32_e32 v2, 16, v3
	v_and_b32_e32 v3, 0xffff0000, v3
	v_lshlrev_b32_e32 v88, 16, v4
	v_and_b32_e32 v89, 0xffff0000, v4
	v_lshlrev_b32_e32 v4, 16, v5
	v_and_b32_e32 v5, 0xffff0000, v5
	v_lshl_add_u64 v[48:49], v[38:39], 0, v[48:49]
	s_waitcnt vmcnt(5)
	v_pk_mul_f32 v[46:47], v[62:63], v[46:47]
	v_pk_mul_f32 v[2:3], v[64:65], v[2:3]
	s_waitcnt vmcnt(3)
	v_pk_fma_f32 v[46:47], v[52:53], v[72:73], v[46:47]
	v_pk_fma_f32 v[2:3], v[54:55], v[74:75], v[2:3]
	s_waitcnt vmcnt(1)
	v_pk_fma_f32 v[46:47], v[50:51], v[80:81], v[46:47]
	v_pk_fma_f32 v[50:51], v[58:59], v[82:83], v[2:3]
	v_mul_f32_e32 v0, 0xbfb8aa3b, v47
	v_mul_f32_e32 v2, 0xbfb8aa3b, v46
	v_exp_f32_e32 v3, v0
	v_exp_f32_e32 v2, v2
	v_pk_mul_f32 v[62:63], v[68:69], v[88:89]
	v_mul_f32_e32 v54, 0xbfb8aa3b, v51
	v_pk_fma_f32 v[52:53], v[56:57], v[76:77], v[62:63]
	v_mul_f32_e32 v56, 0xbfb8aa3b, v50
	v_exp_f32_e32 v55, v54
	v_exp_f32_e32 v54, v56
	v_pk_add_f32 v[2:3], v[2:3], 1.0 op_sel_hi:[1,0]
	s_waitcnt vmcnt(0)
	v_pk_fma_f32 v[52:53], v[60:61], v[84:85], v[52:53]
	v_div_scale_f32 v0, s[6:7], v3, v3, v47
	v_div_scale_f32 v59, s[6:7], v2, v2, v46
	v_rcp_f32_e32 v69, v0
	v_mul_f32_e32 v57, 0xbfb8aa3b, v53
	v_mul_f32_e32 v58, 0xbfb8aa3b, v52
	v_rcp_f32_e32 v72, v59
	v_exp_f32_e32 v57, v57
	v_exp_f32_e32 v56, v58
	v_pk_add_f32 v[54:55], v[54:55], 1.0 op_sel_hi:[1,0]
	v_fma_f32 v76, -v0, v69, 1.0
	v_div_scale_f32 v61, s[8:9], v55, v55, v51
	v_div_scale_f32 v63, s[10:11], v54, v54, v50
	v_rcp_f32_e32 v73, v61
	v_div_scale_f32 v58, vcc, v47, v3, v47
	v_rcp_f32_e32 v74, v63
	v_fma_f32 v77, -v59, v72, 1.0
	v_fmac_f32_e32 v69, v76, v69
	v_pk_add_f32 v[56:57], v[56:57], 1.0 op_sel_hi:[1,0]
	v_div_scale_f32 v60, s[6:7], v46, v2, v46
	v_fmac_f32_e32 v72, v77, v72
	v_mul_f32_e32 v76, v58, v69
	v_div_scale_f32 v65, s[12:13], v57, v57, v53
	v_mul_f32_e32 v77, v60, v72
	v_fma_f32 v83, -v0, v76, v58
	v_rcp_f32_e32 v75, v65
	v_fma_f32 v80, -v61, v73, 1.0
	v_fma_f32 v84, -v59, v77, v60
	v_fmac_f32_e32 v76, v83, v69
	v_div_scale_f32 v62, s[8:9], v51, v55, v51
	v_fma_f32 v81, -v63, v74, 1.0
	v_fmac_f32_e32 v73, v80, v73
	v_fmac_f32_e32 v77, v84, v72
	v_fma_f32 v0, -v0, v76, v58
	v_div_scale_f32 v64, s[10:11], v50, v54, v50
	v_fmac_f32_e32 v74, v81, v74
	v_mul_f32_e32 v80, v62, v73
	v_fma_f32 v58, -v59, v77, v60
	v_div_fmas_f32 v0, v0, v69, v76
	s_mov_b64 vcc, s[6:7]
	v_mul_f32_e32 v81, v64, v74
	v_fma_f32 v85, -v61, v80, v62
	v_div_fixup_f32 v0, v0, v3, v47
	v_div_fmas_f32 v3, v58, v72, v77
	v_fma_f32 v82, -v65, v75, 1.0
	v_fma_f32 v88, -v63, v81, v64
	v_fmac_f32_e32 v80, v85, v73
	v_div_fixup_f32 v2, v3, v2, v46
	v_div_scale_f32 v46, s[6:7], v56, v56, v52
	v_pk_mul_f32 v[4:5], v[70:71], v[4:5]
	v_div_scale_f32 v68, s[12:13], v53, v57, v53
	v_fmac_f32_e32 v75, v82, v75
	v_fmac_f32_e32 v81, v88, v74
	v_fma_f32 v59, -v61, v80, v62
	s_mov_b64 vcc, s[8:9]
	v_rcp_f32_e32 v47, v46
	v_pk_fma_f32 v[4:5], v[44:45], v[78:79], v[4:5]
	v_mul_f32_e32 v82, v68, v75
	v_fma_f32 v60, -v63, v81, v64
	v_div_fmas_f32 v3, v59, v73, v80
	s_mov_b64 vcc, s[10:11]
	v_pk_fma_f32 v[42:43], v[42:43], v[86:87], v[4:5]
	v_fma_f32 v89, -v65, v82, v68
	v_cvt_pk_bf16_f32 v2, v2, v0
	v_div_fixup_f32 v0, v3, v55, v51
	v_div_fmas_f32 v3, v60, v74, v81
	v_mul_f32_e32 v4, 0xbfb8aa3b, v43
	v_div_fixup_f32 v3, v3, v54, v50
	v_fmac_f32_e32 v82, v89, v75
	v_exp_f32_e32 v5, v4
	v_mul_f32_e32 v4, 0xbfb8aa3b, v42
	v_cvt_pk_bf16_f32 v3, v3, v0
	v_fma_f32 v0, -v65, v82, v68
	s_mov_b64 vcc, s[12:13]
	v_fma_f32 v50, -v46, v47, 1.0
	v_exp_f32_e32 v4, v4
	v_div_fmas_f32 v0, v0, v75, v82
	v_fmac_f32_e32 v47, v50, v47
	v_div_scale_f32 v50, vcc, v52, v56, v52
	v_mul_f32_e32 v51, v50, v47
	v_fma_f32 v44, -v46, v51, v50
	v_fmac_f32_e32 v51, v44, v47
	v_pk_add_f32 v[44:45], v[4:5], 1.0 op_sel_hi:[1,0]
	v_fma_f32 v46, -v46, v51, v50
	v_div_scale_f32 v5, s[6:7], v45, v45, v43
	v_rcp_f32_e32 v50, v5
	v_div_fmas_f32 v4, v46, v47, v51
	v_div_fixup_f32 v0, v0, v57, v53
	v_div_fixup_f32 v4, v4, v56, v52
	v_cvt_pk_bf16_f32 v4, v4, v0
	v_fma_f32 v0, -v5, v50, 1.0
	v_fmac_f32_e32 v50, v0, v50
	v_div_scale_f32 v0, vcc, v43, v45, v43
	v_mul_f32_e32 v46, v0, v50
	v_fma_f32 v47, -v5, v46, v0
	v_fmac_f32_e32 v46, v47, v50
	v_fma_f32 v0, -v5, v46, v0
	v_div_scale_f32 v5, s[6:7], v44, v44, v42
	v_rcp_f32_e32 v47, v5
	v_div_fmas_f32 v0, v0, v50, v46
	v_div_fixup_f32 v0, v0, v45, v43
	v_fma_f32 v43, -v5, v47, 1.0
	v_fmac_f32_e32 v47, v43, v47
	v_div_scale_f32 v43, vcc, v42, v44, v42
	v_mul_f32_e32 v45, v43, v47
	v_fma_f32 v46, -v5, v45, v43
	v_fmac_f32_e32 v45, v46, v47
	v_fma_f32 v5, -v5, v45, v43
	v_div_fmas_f32 v5, v5, v47, v45
	v_div_fixup_f32 v5, v5, v44, v42
	v_cvt_pk_bf16_f32 v5, v5, v0
	global_store_dwordx4 v[48:49], v[2:5], off
	s_and_saveexec_b64 s[6:7], s[4:5]
	s_cbranch_execz .LBB0_303
; DI float bf2f(bf16 b) { return __uint_as_float(((unsigned)b) << 16); }
; DI void phase_gdn_prep(const Ctx& c) {
;     ...
;     if (lane < 8) {
;       const float braw = bf2f(Pba[(size_t)tok * 256 + lane]);
;       const float araw = bf2f(Pba[(size_t)tok * 256 + 8 + lane]);
;       BETA[(size_t)tok * 8 + lane] = 1.f / (1.f + __expf(-braw));
;       const float x = araw + dt_b[lane];
;       const float sp = fmaxf(x, 0.f) + __logf(1.f + __expf(-fabsf(x)));
;       G[(size_t)tok * 8 + lane] = -__expf(a_log[lane]) * sp;
;     }
	v_lshlrev_b64 v[2:3], 9, v[6:7]
	v_lshl_add_u64 v[2:3], v[12:13], 0, v[2:3]
	global_load_ushort v0, v[2:3], off
	global_load_ushort v42, v[2:3], off offset:16
	v_lshlrev_b64 v[2:3], 5, v[6:7]
	v_lshl_or_b32 v2, v8, 2, v2
	s_mov_b32 s10, 0x800000
	s_waitcnt vmcnt(1)
	v_lshlrev_b32_e32 v0, 16, v0
	v_mul_f32_e32 v0, 0xbfb8aa3b, v0
	v_exp_f32_e32 v0, v0
	s_nop 0
	v_add_f32_e32 v0, 1.0, v0
	v_div_scale_f32 v7, s[8:9], v0, v0, 1.0
	v_rcp_f32_e32 v43, v7
	v_div_scale_f32 v44, vcc, 1.0, v0, 1.0
	v_readlane_b32 s8, v228, 22
	v_fma_f32 v45, -v7, v43, 1.0
	v_fmac_f32_e32 v43, v45, v43
	v_mul_f32_e32 v45, v44, v43
	v_fma_f32 v46, -v7, v45, v44
	v_fmac_f32_e32 v45, v46, v43
	v_fma_f32 v7, -v7, v45, v44
	v_readlane_b32 s9, v228, 23
	v_div_fmas_f32 v7, v7, v43, v45
	v_div_fixup_f32 v0, v7, v0, 1.0
	v_lshl_add_u64 v[4:5], s[8:9], 0, v[2:3]
	global_store_dword v[4:5], v0, off
	global_load_dword v0, v[14:15], off
	s_nop 0
	global_load_dword v4, v[16:17], off
	s_waitcnt vmcnt(3)
	v_lshlrev_b32_e32 v5, 16, v42
	s_mov_b32 s8, 0xbfb8aa3b
	s_mov_b32 s9, 0x7f800000
	s_waitcnt vmcnt(1)
	v_add_f32_e32 v0, v0, v5
	v_mul_f32_e64 v5, |v0|, s8
	v_exp_f32_e32 v5, v5
	s_mov_b32 s8, 0x3f317217
	s_waitcnt vmcnt(0)
	v_mul_f32_e32 v4, 0x3fb8aa3b, v4
	v_exp_f32_e32 v4, v4
	v_add_f32_e32 v5, 1.0, v5
	v_cmp_gt_f32_e32 vcc, s10, v5
	v_max_f32_e32 v0, 0, v0
	s_nop 0
	v_cndmask_b32_e64 v7, 0, 32, vcc
	v_ldexp_f32 v5, v5, v7
	v_log_f32_e32 v5, v5
	v_cndmask_b32_e32 v7, 0, v191, vcc
	v_mul_f32_e32 v42, 0x3f317217, v5
	v_fma_f32 v42, v5, s8, -v42
	v_fmac_f32_e32 v42, 0x3377d1cf, v5
	v_fmac_f32_e32 v42, 0x3f317217, v5
	v_cmp_lt_f32_e64 vcc, |v5|, s9
	v_readlane_b32 s8, v228, 24
	v_readlane_b32 s9, v228, 25
	v_cndmask_b32_e32 v5, v5, v42, vcc
	v_sub_f32_e32 v5, v5, v7
	v_add_f32_e32 v0, v0, v5
	v_mul_f32_e64 v0, v0, -v4
	v_lshl_add_u64 v[2:3], s[8:9], 0, v[2:3]
	global_store_dword v[2:3], v0, off
	s_branch .LBB0_303

; #define MFMA32(a, b, c) __builtin_amdgcn_mfma_f32_32x32x16_bf16((a), (b), (c), 0, 0, 0)
; DI void attn_item(const Ctx& c, int item) {
;     ...
;   for (int kt = 0; kt < ntile; ++kt) {
;     const bf16* ks_ = Ks + (kt & 1) * KSZ; const bf16* vs_ = Vs + (kt & 1) * VSZ;
;     f32x16 s[2];
; #pragma unroll
;     for (int kg = 0; kg < 2; ++kg)
; #pragma unroll
;       for (int i = 0; i < 16; ++i) s[kg][i] = 0.f;
; #pragma unroll
;     for (int ks = 0; ks < 12; ++ks)
; #pragma unroll
;       for (int kg = 0; kg < 2; ++kg) {
;         const bf16x8 a = *(const bf16x8*)(ks_ + (kg * 32 + r32) * 200 + ks * 16 + 8 * hh);
;         s[kg] = MFMA32(a, bq[ks], s[kg]);
;       }
;     float mx = s[0][0];
; #pragma unroll
;     for (int kg = 0; kg < 2; ++kg)
; #pragma unroll
;       for (int i = 0; i < 16; ++i) mx = fmaxf(mx, s[kg][i]);
;     mx = fmaxf(mx, __shfl_xor(mx, 32));
;     const float mn = fmaxf(m_, mx * sc);
;     const float alpha = __builtin_amdgcn_exp2f(m_ - mn);
;     m_ = mn;
;     float ps = 0.f;
; #pragma unroll
;     for (int kg = 0; kg < 2; ++kg)
; #pragma unroll
;       for (int i = 0; i < 16; ++i) { s[kg][i] = __builtin_amdgcn_exp2f(s[kg][i] * sc - mn); ps += s[kg][i]; }
;     l_ = l_ * alpha + ps;
;     if (__builtin_amdgcn_ballot_w64(alpha != 1.0f) != 0ull) {
; #pragma unroll
;       for (int dt = 0; dt < 4; ++dt)
; #pragma unroll
;         for (int i = 0; i < 16; ++i) oacc[dt][i] *= alpha;
;     }
.LBB0_547:
	s_and_b32 s0, s4, 1
	s_mul_i32 s1, s0, 0x6400
	v_mov_b32_e32 v0, v211
	v_add_u32_e32 v211, s1, v208
	ds_read_b128 v[230:233], v211
	ds_read_b128 v[234:237], v211 offset:12800
	ds_read_b128 v[238:241], v211 offset:32
	ds_read_b128 v[242:245], v211 offset:12832
	s_waitcnt lgkmcnt(3)
	v_mfma_f32_32x32x16_bf16 v[82:97], v[230:233], v[98:101], 0
	ds_read_b128 v[230:233], v211 offset:64
	s_waitcnt lgkmcnt(3)
	v_mfma_f32_32x32x16_bf16 v[66:81], v[234:237], v[98:101], 0
	ds_read_b128 v[234:237], v211 offset:12864
	s_waitcnt lgkmcnt(3)
	v_mfma_f32_32x32x16_bf16 v[82:97], v[238:241], v[102:105], v[82:97]
	ds_read_b128 v[238:241], v211 offset:96
	s_waitcnt lgkmcnt(3)
	v_mfma_f32_32x32x16_bf16 v[66:81], v[242:245], v[102:105], v[66:81]
	ds_read_b128 v[242:245], v211 offset:12896
	s_waitcnt lgkmcnt(3)
	v_mfma_f32_32x32x16_bf16 v[82:97], v[230:233], v[106:109], v[82:97]
	ds_read_b128 v[230:233], v211 offset:128
	s_waitcnt lgkmcnt(3)
	v_mfma_f32_32x32x16_bf16 v[66:81], v[234:237], v[106:109], v[66:81]
	ds_read_b128 v[234:237], v211 offset:12928
	s_waitcnt lgkmcnt(3)
	v_mfma_f32_32x32x16_bf16 v[82:97], v[238:241], v[110:113], v[82:97]
	ds_read_b128 v[238:241], v211 offset:160
	s_waitcnt lgkmcnt(3)
	v_mfma_f32_32x32x16_bf16 v[66:81], v[242:245], v[110:113], v[66:81]
	ds_read_b128 v[242:245], v211 offset:12960
	s_waitcnt lgkmcnt(3)
	v_mfma_f32_32x32x16_bf16 v[82:97], v[230:233], v[114:117], v[82:97]
	ds_read_b128 v[230:233], v211 offset:192
	s_waitcnt lgkmcnt(3)
	v_mfma_f32_32x32x16_bf16 v[66:81], v[234:237], v[114:117], v[66:81]
	ds_read_b128 v[234:237], v211 offset:12992
	s_waitcnt lgkmcnt(3)
	v_mfma_f32_32x32x16_bf16 v[82:97], v[238:241], v[118:121], v[82:97]
	ds_read_b128 v[238:241], v211 offset:224
	s_waitcnt lgkmcnt(3)
	v_mfma_f32_32x32x16_bf16 v[66:81], v[242:245], v[118:121], v[66:81]
	ds_read_b128 v[242:245], v211 offset:13024
	s_waitcnt lgkmcnt(3)
	v_mfma_f32_32x32x16_bf16 v[82:97], v[230:233], v[122:125], v[82:97]
	ds_read_b128 v[230:233], v211 offset:256
	s_waitcnt lgkmcnt(3)
	v_mfma_f32_32x32x16_bf16 v[66:81], v[234:237], v[122:125], v[66:81]
	ds_read_b128 v[234:237], v211 offset:13056
	s_waitcnt lgkmcnt(3)
	v_mfma_f32_32x32x16_bf16 v[82:97], v[238:241], v[126:129], v[82:97]
	ds_read_b128 v[238:241], v211 offset:288
	s_waitcnt lgkmcnt(3)
	v_mfma_f32_32x32x16_bf16 v[66:81], v[242:245], v[126:129], v[66:81]
	ds_read_b128 v[242:245], v211 offset:13088
	s_waitcnt lgkmcnt(3)
	v_mfma_f32_32x32x16_bf16 v[82:97], v[230:233], v[130:133], v[82:97]
	ds_read_b128 v[230:233], v211 offset:320
	s_waitcnt lgkmcnt(3)
	v_mfma_f32_32x32x16_bf16 v[66:81], v[234:237], v[130:133], v[66:81]
	ds_read_b128 v[234:237], v211 offset:13120
	s_waitcnt lgkmcnt(3)
	v_mfma_f32_32x32x16_bf16 v[82:97], v[238:241], v[134:137], v[82:97]
	ds_read_b128 v[238:241], v211 offset:352
	s_waitcnt lgkmcnt(3)
	v_mfma_f32_32x32x16_bf16 v[66:81], v[242:245], v[134:137], v[66:81]
	ds_read_b128 v[242:245], v211 offset:13152
	s_waitcnt lgkmcnt(3)
	v_mfma_f32_32x32x16_bf16 v[82:97], v[230:233], v[138:141], v[82:97]
	s_waitcnt lgkmcnt(2)
	v_mfma_f32_32x32x16_bf16 v[66:81], v[234:237], v[138:141], v[66:81]
	s_waitcnt lgkmcnt(1)
	v_mfma_f32_32x32x16_bf16 v[82:97], v[238:241], v[142:145], v[82:97]
	s_waitcnt lgkmcnt(0)
	v_mfma_f32_32x32x16_bf16 v[66:81], v[242:245], v[142:145], v[66:81]
	s_mulk_i32 s0, 0x4800
	v_add_u32_e32 v224, s0, v209
	ds_read_b128 v[230:233], v224 offset:51200
	ds_read_b128 v[234:237], v224 offset:55808
	ds_read_b128 v[238:241], v224 offset:60416
	ds_read_b128 v[242:245], v224 offset:65024
	ds_read_b128 v[246:249], v224 offset:51232
	s_nop 1
	v_max_f32_e32 v211, v83, v83
	v_max_f32_e32 v212, v82, v82
	v_max_f32_e32 v211, v212, v211
	v_max3_f32 v211, v211, v84, v85
	v_max3_f32 v211, v211, v86, v87
	v_max3_f32 v211, v211, v88, v89
	v_max3_f32 v211, v211, v90, v91
	v_max3_f32 v211, v211, v92, v93
	v_max3_f32 v211, v211, v94, v95
	v_max3_f32 v211, v211, v96, v97
	v_max3_f32 v211, v211, v66, v67
	v_max3_f32 v211, v211, v68, v69
	v_max3_f32 v211, v211, v70, v71
	v_max3_f32 v211, v211, v72, v73
	v_max3_f32 v211, v211, v74, v75
	v_max3_f32 v211, v211, v76, v77
	v_max3_f32 v211, v211, v78, v79
	v_max3_f32 v211, v211, v80, v81
	ds_bpermute_b32 v212, v207, v211
	s_waitcnt lgkmcnt(0)
	v_max_f32_e32 v212, v212, v212
	v_max_f32_e32 v211, v211, v212
	v_mul_f32_e32 v211, 0x3dd53b94, v211
	v_max_f32_e32 v212, v0, v0
	v_max_f32_e32 v211, v212, v211
	v_sub_f32_e32 v0, v0, v211
	v_exp_f32_e32 v0, v0
	s_nop 0
	v_cmp_neq_f32_e32 vcc, 1.0, v0
	s_cbranch_vccz .LBB0_549
	v_pk_mul_f32 v[64:65], v[64:65], v[0:1] op_sel_hi:[1,0]
	v_pk_mul_f32 v[62:63], v[62:63], v[0:1] op_sel_hi:[1,0]
	v_pk_mul_f32 v[60:61], v[60:61], v[0:1] op_sel_hi:[1,0]
	v_pk_mul_f32 v[58:59], v[58:59], v[0:1] op_sel_hi:[1,0]
	v_pk_mul_f32 v[56:57], v[56:57], v[0:1] op_sel_hi:[1,0]
	v_pk_mul_f32 v[54:55], v[54:55], v[0:1] op_sel_hi:[1,0]
	v_pk_mul_f32 v[52:53], v[52:53], v[0:1] op_sel_hi:[1,0]
	v_pk_mul_f32 v[50:51], v[50:51], v[0:1] op_sel_hi:[1,0]
	v_pk_mul_f32 v[48:49], v[48:49], v[0:1] op_sel_hi:[1,0]
	v_pk_mul_f32 v[46:47], v[46:47], v[0:1] op_sel_hi:[1,0]
	v_pk_mul_f32 v[44:45], v[44:45], v[0:1] op_sel_hi:[1,0]
	v_pk_mul_f32 v[42:43], v[42:43], v[0:1] op_sel_hi:[1,0]
	v_pk_mul_f32 v[40:41], v[40:41], v[0:1] op_sel_hi:[1,0]
	v_pk_mul_f32 v[38:39], v[38:39], v[0:1] op_sel_hi:[1,0]
	v_pk_mul_f32 v[36:37], v[36:37], v[0:1] op_sel_hi:[1,0]
	v_pk_mul_f32 v[34:35], v[34:35], v[0:1] op_sel_hi:[1,0]
	v_pk_mul_f32 v[32:33], v[32:33], v[0:1] op_sel_hi:[1,0]
	v_pk_mul_f32 v[30:31], v[30:31], v[0:1] op_sel_hi:[1,0]
	v_pk_mul_f32 v[28:29], v[28:29], v[0:1] op_sel_hi:[1,0]
	v_pk_mul_f32 v[26:27], v[26:27], v[0:1] op_sel_hi:[1,0]
	v_pk_mul_f32 v[24:25], v[24:25], v[0:1] op_sel_hi:[1,0]
	v_pk_mul_f32 v[22:23], v[22:23], v[0:1] op_sel_hi:[1,0]
	v_pk_mul_f32 v[20:21], v[20:21], v[0:1] op_sel_hi:[1,0]
	v_pk_mul_f32 v[18:19], v[18:19], v[0:1] op_sel_hi:[1,0]
	v_pk_mul_f32 v[16:17], v[16:17], v[0:1] op_sel_hi:[1,0]
	v_pk_mul_f32 v[14:15], v[14:15], v[0:1] op_sel_hi:[1,0]
	v_pk_mul_f32 v[12:13], v[12:13], v[0:1] op_sel_hi:[1,0]
	v_pk_mul_f32 v[10:11], v[10:11], v[0:1] op_sel_hi:[1,0]
	v_pk_mul_f32 v[8:9], v[8:9], v[0:1] op_sel_hi:[1,0]
	v_pk_mul_f32 v[6:7], v[6:7], v[0:1] op_sel_hi:[1,0]
	v_pk_mul_f32 v[4:5], v[4:5], v[0:1] op_sel_hi:[1,0]
	v_pk_mul_f32 v[2:3], v[2:3], v[0:1] op_sel_hi:[1,0]
; #define MFMA32(a, b, c) __builtin_amdgcn_mfma_f32_32x32x16_bf16((a), (b), (c), 0, 0, 0)
; DI void attn_item(const Ctx& c, int item) {
;     ...
;     float ps = 0.f;
; #pragma unroll
;     for (int kg = 0; kg < 2; ++kg)
; #pragma unroll
;       for (int i = 0; i < 16; ++i) { s[kg][i] = __builtin_amdgcn_exp2f(s[kg][i] * sc - mn); ps += s[kg][i]; }
;     l_ = l_ * alpha + ps;
;     if (__builtin_amdgcn_ballot_w64(alpha != 1.0f) != 0ull) {
; #pragma unroll
;       for (int dt = 0; dt < 4; ++dt)
; #pragma unroll
;         for (int i = 0; i < 16; ++i) oacc[dt][i] *= alpha;
;     }
; #pragma unroll
;     for (int kg = 0; kg < 2; ++kg)
; #pragma unroll
;       for (int st = 0; st < 2; ++st) {
;         u32x4 pb;
;         pb[0] = pack2(s[kg][8 * st + 0], s[kg][8 * st + 1]); pb[1] = pack2(s[kg][8 * st + 2], s[kg][8 * st + 3]);
;         pb[2] = pack2(s[kg][8 * st + 4], s[kg][8 * st + 5]); pb[3] = pack2(s[kg][8 * st + 6], s[kg][8 * st + 7]);
;         const bf16x8 pbv = __builtin_bit_cast(bf16x8, pb);
; #pragma unroll
;         for (int dt = 0; dt < 4; ++dt) {
;           const bf16x8 av = *(const bf16x8*)(vs_ + (dt * 32 + r32) * 72 + kg * 32 + 16 * st + 8 * hh);
;           oacc[dt] = MFMA32(av, pbv, oacc[dt]);
;         }
;       }
;     if (kt + 1 < ntile) ATT_STORE((kt + 1) & 1)
.LBB0_549:
	v_fma_f32 v82, v82, s7, -v211
	v_fma_f32 v83, v83, s7, -v211
	v_fma_f32 v84, v84, s7, -v211
	v_fma_f32 v85, v85, s7, -v211
	v_fma_f32 v86, v86, s7, -v211
	v_fma_f32 v87, v87, s7, -v211
	v_fma_f32 v88, v88, s7, -v211
	v_fma_f32 v89, v89, s7, -v211
	v_exp_f32_e32 v82, v82
	v_exp_f32_e32 v83, v83
	v_exp_f32_e32 v84, v84
	v_exp_f32_e32 v85, v85
	v_exp_f32_e32 v86, v86
	v_exp_f32_e32 v87, v87
	v_exp_f32_e32 v88, v88
	v_exp_f32_e32 v89, v89
	s_nop 0
	v_cvt_pk_bf16_f32 v212, v82, v83
	v_cvt_pk_bf16_f32 v213, v84, v85
	v_cvt_pk_bf16_f32 v214, v86, v87
	v_cvt_pk_bf16_f32 v215, v88, v89
	s_nop 0
	s_waitcnt lgkmcnt(4)
	v_mfma_f32_32x32x16_bf16 v[50:65], v[230:233], v[212:215], v[50:65]
	ds_read_b128 v[230:233], v224 offset:55840
	v_fma_f32 v90, v90, s7, -v211
	v_fma_f32 v91, v91, s7, -v211
	v_fma_f32 v92, v92, s7, -v211
	v_fma_f32 v93, v93, s7, -v211
	v_exp_f32_e32 v90, v90
	v_exp_f32_e32 v91, v91
	s_waitcnt lgkmcnt(4)
	v_mfma_f32_32x32x16_bf16 v[34:49], v[234:237], v[212:215], v[34:49]
	ds_read_b128 v[234:237], v224 offset:60448
	v_fma_f32 v94, v94, s7, -v211
	v_fma_f32 v95, v95, s7, -v211
	v_fma_f32 v96, v96, s7, -v211
	v_fma_f32 v97, v97, s7, -v211
	v_exp_f32_e32 v92, v92
	v_exp_f32_e32 v93, v93
	s_waitcnt lgkmcnt(4)
	v_mfma_f32_32x32x16_bf16 v[18:33], v[238:241], v[212:215], v[18:33]
	ds_read_b128 v[238:241], v224 offset:65056
	v_exp_f32_e32 v94, v94
	v_exp_f32_e32 v95, v95
	v_exp_f32_e32 v96, v96
	v_exp_f32_e32 v97, v97
	v_cvt_pk_bf16_f32 v250, v90, v91
	v_cvt_pk_bf16_f32 v251, v92, v93
	s_waitcnt lgkmcnt(4)
	v_mfma_f32_32x32x16_bf16 v[2:17], v[242:245], v[212:215], v[2:17]
	ds_read_b128 v[242:245], v224 offset:51264
	v_cvt_pk_bf16_f32 v252, v94, v95
	v_cvt_pk_bf16_f32 v253, v96, v97
	s_nop 0
	s_waitcnt lgkmcnt(4)
	v_mfma_f32_32x32x16_bf16 v[50:65], v[246:249], v[250:253], v[50:65]
	ds_read_b128 v[246:249], v224 offset:55872
	v_fma_f32 v66, v66, s7, -v211
	v_fma_f32 v67, v67, s7, -v211
	v_fma_f32 v68, v68, s7, -v211
	v_fma_f32 v69, v69, s7, -v211
	v_exp_f32_e32 v66, v66
	v_exp_f32_e32 v67, v67
	s_waitcnt lgkmcnt(4)
	v_mfma_f32_32x32x16_bf16 v[34:49], v[230:233], v[250:253], v[34:49]
	ds_read_b128 v[230:233], v224 offset:60480
	v_fma_f32 v70, v70, s7, -v211
	v_fma_f32 v71, v71, s7, -v211
	v_fma_f32 v72, v72, s7, -v211
	v_fma_f32 v73, v73, s7, -v211
	v_exp_f32_e32 v68, v68
	v_exp_f32_e32 v69, v69
	s_waitcnt lgkmcnt(4)
	v_mfma_f32_32x32x16_bf16 v[18:33], v[234:237], v[250:253], v[18:33]
	ds_read_b128 v[234:237], v224 offset:65088
	v_exp_f32_e32 v70, v70
	v_exp_f32_e32 v71, v71
	v_exp_f32_e32 v72, v72
	v_exp_f32_e32 v73, v73
	v_cvt_pk_bf16_f32 v212, v66, v67
	v_cvt_pk_bf16_f32 v213, v68, v69
	s_waitcnt lgkmcnt(4)
	v_mfma_f32_32x32x16_bf16 v[2:17], v[238:241], v[250:253], v[2:17]
	ds_read_b128 v[238:241], v224 offset:51296
	v_cvt_pk_bf16_f32 v214, v70, v71
	v_cvt_pk_bf16_f32 v215, v72, v73
	s_nop 0
	s_waitcnt lgkmcnt(4)
	v_mfma_f32_32x32x16_bf16 v[50:65], v[242:245], v[212:215], v[50:65]
	ds_read_b128 v[242:245], v224 offset:55904
	v_fma_f32 v74, v74, s7, -v211
	v_fma_f32 v75, v75, s7, -v211
	v_fma_f32 v76, v76, s7, -v211
	v_fma_f32 v77, v77, s7, -v211
	v_exp_f32_e32 v74, v74
	v_exp_f32_e32 v75, v75
	s_waitcnt lgkmcnt(4)
	v_mfma_f32_32x32x16_bf16 v[34:49], v[246:249], v[212:215], v[34:49]
	ds_read_b128 v[246:249], v224 offset:60512
	v_fma_f32 v78, v78, s7, -v211
	v_fma_f32 v79, v79, s7, -v211
	v_fma_f32 v80, v80, s7, -v211
	v_fma_f32 v81, v81, s7, -v211
	v_exp_f32_e32 v76, v76
	v_exp_f32_e32 v77, v77
	s_waitcnt lgkmcnt(4)
	v_mfma_f32_32x32x16_bf16 v[18:33], v[230:233], v[212:215], v[18:33]
	ds_read_b128 v[230:233], v224 offset:65120
	v_exp_f32_e32 v78, v78
	v_exp_f32_e32 v79, v79
	v_exp_f32_e32 v80, v80
	v_exp_f32_e32 v81, v81
	v_cvt_pk_bf16_f32 v250, v74, v75
	v_cvt_pk_bf16_f32 v251, v76, v77
	s_waitcnt lgkmcnt(4)
	v_mfma_f32_32x32x16_bf16 v[2:17], v[234:237], v[212:215], v[2:17]
	v_cvt_pk_bf16_f32 v252, v78, v79
	v_cvt_pk_bf16_f32 v253, v80, v81
	s_nop 0
	s_waitcnt lgkmcnt(3)
	v_mfma_f32_32x32x16_bf16 v[50:65], v[238:241], v[250:253], v[50:65]
	v_add_f32_e32 v82, v86, v82
	v_add_f32_e32 v83, v87, v83
	v_add_f32_e32 v84, v88, v84
	v_add_f32_e32 v85, v89, v85
	v_add_f32_e32 v82, v90, v82
	v_add_f32_e32 v83, v91, v83
	v_add_f32_e32 v84, v92, v84
	s_waitcnt lgkmcnt(2)
	v_mfma_f32_32x32x16_bf16 v[34:49], v[242:245], v[250:253], v[34:49]
	v_add_f32_e32 v85, v93, v85
	v_add_f32_e32 v82, v94, v82
	v_add_f32_e32 v83, v95, v83
	v_add_f32_e32 v84, v96, v84
	v_add_f32_e32 v85, v97, v85
	v_add_f32_e32 v82, v66, v82
	v_add_f32_e32 v83, v67, v83
	s_waitcnt lgkmcnt(1)
	v_mfma_f32_32x32x16_bf16 v[18:33], v[246:249], v[250:253], v[18:33]
	v_add_f32_e32 v84, v68, v84
	v_add_f32_e32 v85, v69, v85
	v_add_f32_e32 v82, v70, v82
	v_add_f32_e32 v83, v71, v83
	v_add_f32_e32 v84, v72, v84
	v_add_f32_e32 v85, v73, v85
	v_add_f32_e32 v82, v74, v82
	s_waitcnt lgkmcnt(0)
	v_mfma_f32_32x32x16_bf16 v[2:17], v[230:233], v[250:253], v[2:17]
	v_add_f32_e32 v83, v75, v83
	v_add_f32_e32 v84, v76, v84
	v_add_f32_e32 v85, v77, v85
	v_add_f32_e32 v82, v78, v82
	v_add_f32_e32 v83, v79, v83
	v_add_f32_e32 v84, v80, v84
	v_add_f32_e32 v85, v81, v85
	v_add_f32_e32 v82, v82, v83
	v_add_f32_e32 v84, v84, v85
	v_add_f32_e32 v66, v82, v84
	s_add_i32 s0, s4, 1
	s_cmp_ge_u32 s0, s8
	s_cbranch_scc1 .LBB0_551
	s_bitcmp1_b32 s0, 0
	s_cselect_b32 s1, 0x6400, 0
	s_cselect_b32 s5, 0x4800, 0
	s_addk_i32 s1, 0x50
	v_lshlrev_b32_e32 v212, 1, v168
	v_add3_u32 v212, s1, v169, v212
	s_waitcnt vmcnt(4)
	ds_write_b128 v212, v[146:149]
	v_lshlrev_b32_e32 v212, 1, v170
	v_add3_u32 v212, s1, v171, v212
	s_waitcnt vmcnt(3)
	ds_write_b128 v212, v[150:153]
	v_lshlrev_b32_e32 v212, 1, v172
	v_add3_u32 v212, s1, v173, v212
	s_waitcnt vmcnt(2)
	ds_write_b128 v212, v[154:157]
	v_add_u32_e32 v212, s5, v206
	v_add_u32_e32 v213, 0xc800, v212
	v_add_u32_e32 v212, 0xe800, v212
	s_waitcnt vmcnt(1)
	ds_write2_b64 v213, v[158:159], v[160:161] offset1:2
	s_waitcnt vmcnt(0)
	ds_write2_b64 v212, v[162:163], v[164:165] offset0:128 offset1:130

; #define ATT_LOAD(KT)                                                                                    \
;   { _Pragma("unroll") for (int r = 0; r < 3; ++r) rk[r] = *(const u32x4*)(Kg + (size_t)((KT) * 64 + krow[r]) * 768 + kseg[r]); \
;     _Pragma("unroll") for (int r = 0; r < 2; ++r) rv[r] = *(const u32x4*)(Vg + (size_t)(vrow0 + 64 * r) * L + (KT) * 64 + vseg); }
; DI void attn_item(const Ctx& c, int item) {
;     ...
;       for (int i = 0; i < 16; ++i) { s[kg][i] = __builtin_amdgcn_exp2f(s[kg][i] * sc - mn); ps += s[kg][i]; }
;     l_ = l_ * alpha + ps;
;     ...
;     if (kt + 1 < ntile) ATT_STORE((kt + 1) & 1)
;     if (kt + 2 < ntile) ATT_LOAD(kt + 2)
;     __syncthreads();
;   }
.LBB0_553:
	s_add_i32 s82, s82, 64
	v_fmac_f32_e32 v66, v210, v0
	s_cmp_lg_u32 s8, s0
	s_waitcnt lgkmcnt(0)
	s_barrier
	s_cbranch_scc0 .LBB0_555
	v_mov_b32_e32 v210, v66
	s_mov_b32 s4, s0
	s_branch .LBB0_547

; DI float cos2pi(float x) { return __builtin_amdgcn_cosf(x); }
; DI float sin2pi(float x) { return __builtin_amdgcn_sinf(x); }
; DI void hyena_item(const Ctx& c, int ch, float* red) {
;     ...
;     for (int p = 0; p < 2; ++p) {
; #pragma unroll 4
;       for (int n = tid; n < L; n += NTHR) {
;         const float hfn = HFB[n].x;
;         const float hbm = (n > 0) ? HFB[L - n].y : 0.f;
;         if (p == 0) buf0[n] = make_float2(hfn + hbm, 0.f);
;         else {
;           const float v = hfn - hbm; const float fr = (float)n * i2L;
;           buf0[n] = make_float2(v * cos2pi(fr), -v * sin2pi(fr));
;         }
;       }
;       __syncthreads();
.LBB0_581:
	s_mov_b64 s[28:29], 0x1000
	s_or_b64 exec, exec, s[0:1]
	s_waitcnt vmcnt(63) expcnt(7) lgkmcnt(15)
	s_barrier
	s_and_saveexec_b64 s[0:1], s[42:43]
	s_cbranch_execz .LBB0_599
	v_mov_b32_e32 v230, v34
	v_mov_b32_e32 v231, v34
	v_mov_b32_e32 v242, v92
	v_mov_b32_e32 v245, 0
	v_mov_b32_e32 v246, s86
	v_add_u32_e32 v246, -1, v246
	s_lshr_b32 s101, s86, 11
	s_mov_b32 s100, 0
.Lhfb_p0_loop:
	v_lshlrev_b32_e32 v240, 3, v230
	v_sub_u32_e32 v241, s86, v230
	v_and_b32_e32 v241, v246, v241
	v_lshlrev_b32_e32 v241, 3, v241
	global_load_dword v232, v240, s[36:37]
	global_load_dword v236, v241, s[36:37] offset:4
	v_add_u32_e32 v230, 0x200, v230
	v_lshlrev_b32_e32 v240, 3, v230
	v_sub_u32_e32 v241, s86, v230
	v_and_b32_e32 v241, v246, v241
	v_lshlrev_b32_e32 v241, 3, v241
	global_load_dword v233, v240, s[36:37]
	global_load_dword v237, v241, s[36:37] offset:4
	v_add_u32_e32 v230, 0x200, v230
	v_lshlrev_b32_e32 v240, 3, v230
	v_sub_u32_e32 v241, s86, v230
	v_and_b32_e32 v241, v246, v241
	v_lshlrev_b32_e32 v241, 3, v241
	global_load_dword v234, v240, s[36:37]
	global_load_dword v238, v241, s[36:37] offset:4
	v_add_u32_e32 v230, 0x200, v230
	v_lshlrev_b32_e32 v240, 3, v230
	v_sub_u32_e32 v241, s86, v230
	v_and_b32_e32 v241, v246, v241
	v_lshlrev_b32_e32 v241, 3, v241
	global_load_dword v235, v240, s[36:37]
	global_load_dword v239, v241, s[36:37] offset:4
	v_add_u32_e32 v230, 0x200, v230
	s_waitcnt vmcnt(0)
	v_cmp_eq_u32_e32 vcc, 0, v231
	s_nop 1
	v_cndmask_b32_e64 v236, v236, 0, vcc
	v_add_f32_e32 v244, v232, v236
	v_add_u32_e32 v231, 0x200, v231
	ds_write_b64 v242, v[244:245]
	v_add_u32_e32 v242, 0x1000, v242
	v_cmp_eq_u32_e32 vcc, 0, v231
	s_nop 1
	v_cndmask_b32_e64 v237, v237, 0, vcc
	v_add_f32_e32 v244, v233, v237
	v_add_u32_e32 v231, 0x200, v231
	ds_write_b64 v242, v[244:245]
	v_add_u32_e32 v242, 0x1000, v242
	v_cmp_eq_u32_e32 vcc, 0, v231
	s_nop 1
	v_cndmask_b32_e64 v238, v238, 0, vcc
	v_add_f32_e32 v244, v234, v238
	v_add_u32_e32 v231, 0x200, v231
	ds_write_b64 v242, v[244:245]
	v_add_u32_e32 v242, 0x1000, v242
	v_cmp_eq_u32_e32 vcc, 0, v231
	s_nop 1
	v_cndmask_b32_e64 v239, v239, 0, vcc
	v_add_f32_e32 v244, v235, v239
	v_add_u32_e32 v231, 0x200, v231
	ds_write_b64 v242, v[244:245]
	v_add_u32_e32 v242, 0x1000, v242
	s_add_i32 s100, s100, 1
	s_cmp_lg_u32 s100, s101
	s_cbranch_scc1 .Lhfb_p0_loop

; DI float cos2pi(float x) { return __builtin_amdgcn_cosf(x); }
; DI float sin2pi(float x) { return __builtin_amdgcn_sinf(x); }
; DI void hyena_item(const Ctx& c, int ch, float* red) {
;     ...
;       for (int n = tid; n < L; n += NTHR) {
;         const float hfn = HFB[n].x;
;         const float hbm = (n > 0) ? HFB[L - n].y : 0.f;
;         if (p == 0) buf0[n] = make_float2(hfn + hbm, 0.f);
;         else {
;           const float v = hfn - hbm; const float fr = (float)n * i2L;
;           buf0[n] = make_float2(v * cos2pi(fr), -v * sin2pi(fr));
;         }
.Lhfb_p1_loop:
	v_lshlrev_b32_e32 v240, 3, v230
	v_sub_u32_e32 v241, s86, v230
	v_and_b32_e32 v241, v246, v241
	v_lshlrev_b32_e32 v241, 3, v241
	global_load_dword v232, v240, s[36:37]
	global_load_dword v236, v241, s[36:37] offset:4
	v_add_u32_e32 v230, 0x200, v230
	v_lshlrev_b32_e32 v240, 3, v230
	v_sub_u32_e32 v241, s86, v230
	v_and_b32_e32 v241, v246, v241
	v_lshlrev_b32_e32 v241, 3, v241
	global_load_dword v233, v240, s[36:37]
	global_load_dword v237, v241, s[36:37] offset:4
	v_add_u32_e32 v230, 0x200, v230
	v_lshlrev_b32_e32 v240, 3, v230
	v_sub_u32_e32 v241, s86, v230
	v_and_b32_e32 v241, v246, v241
	v_lshlrev_b32_e32 v241, 3, v241
	global_load_dword v234, v240, s[36:37]
	global_load_dword v238, v241, s[36:37] offset:4
	v_add_u32_e32 v230, 0x200, v230
	v_lshlrev_b32_e32 v240, 3, v230
	v_sub_u32_e32 v241, s86, v230
	v_and_b32_e32 v241, v246, v241
	v_lshlrev_b32_e32 v241, 3, v241
	global_load_dword v235, v240, s[36:37]
	global_load_dword v239, v241, s[36:37] offset:4
	v_add_u32_e32 v230, 0x200, v230
	s_waitcnt vmcnt(0)
	v_cmp_eq_u32_e32 vcc, 0, v231
	v_cvt_f32_i32_e32 v247, v231
	v_mul_f32_e32 v247, v199, v247
	v_cndmask_b32_e64 v236, v236, 0, vcc
	v_cos_f32_e32 v248, v247
	v_sin_f32_e32 v249, v247
	v_sub_f32_e32 v243, v232, v236
	v_add_u32_e32 v231, 0x200, v231
	v_mul_f32_e64 v245, -v243, v249
	v_mul_f32_e32 v244, v248, v243
	ds_write_b64 v242, v[244:245]
	v_add_u32_e32 v242, 0x1000, v242
	v_cmp_eq_u32_e32 vcc, 0, v231
	v_cvt_f32_i32_e32 v247, v231
	v_mul_f32_e32 v247, v199, v247
	v_cndmask_b32_e64 v237, v237, 0, vcc
	v_cos_f32_e32 v248, v247
	v_sin_f32_e32 v249, v247
	v_sub_f32_e32 v243, v233, v237
	v_add_u32_e32 v231, 0x200, v231
	v_mul_f32_e64 v245, -v243, v249
	v_mul_f32_e32 v244, v248, v243
	ds_write_b64 v242, v[244:245]
	v_add_u32_e32 v242, 0x1000, v242
	v_cmp_eq_u32_e32 vcc, 0, v231
	v_cvt_f32_i32_e32 v247, v231
	v_mul_f32_e32 v247, v199, v247
	v_cndmask_b32_e64 v238, v238, 0, vcc
	v_cos_f32_e32 v248, v247
	v_sin_f32_e32 v249, v247
	v_sub_f32_e32 v243, v234, v238
	v_add_u32_e32 v231, 0x200, v231
	v_mul_f32_e64 v245, -v243, v249
	v_mul_f32_e32 v244, v248, v243
	ds_write_b64 v242, v[244:245]
	v_add_u32_e32 v242, 0x1000, v242
	v_cmp_eq_u32_e32 vcc, 0, v231
	v_cvt_f32_i32_e32 v247, v231
	v_mul_f32_e32 v247, v199, v247
	v_cndmask_b32_e64 v239, v239, 0, vcc
	v_cos_f32_e32 v248, v247
	v_sin_f32_e32 v249, v247
	v_sub_f32_e32 v243, v235, v239
	v_add_u32_e32 v231, 0x200, v231
	v_mul_f32_e64 v245, -v243, v249
	v_mul_f32_e32 v244, v248, v243
	ds_write_b64 v242, v[244:245]
	v_add_u32_e32 v242, 0x1000, v242
	s_add_i32 s100, s100, 1
	s_cmp_lg_u32 s100, s101
	s_cbranch_scc1 .Lhfb_p1_loop
